# v1 + grid barrier moved to after mixB so gates and fnetw tiles share one phase (fnetw on blocks idle in the last gates round)
# speedup vs baseline: 1.0040x; 1.0040x over previous
_Z14fwd_megakernel6Paramsiii:
	s_mov_b32 s98, 0
	v_and_b32_e32 v1, 0x3ff, v0
	v_writelane_b32 v248, s2, 0
	s_load_dwordx16 s[68:83], s[0:1], 0x80
	s_load_dword s2, s[0:1], 0xd8
	s_load_dwordx2 s[50:51], s[0:1], 0xd0
	v_cmp_eq_u32_e64 s[4:5], 0, v1
	s_waitcnt lgkmcnt(0)
	v_writelane_b32 v248, s2, 1
	s_add_u32 s2, s0, 0xd0
	s_addc_u32 s3, s1, 0
	v_writelane_b32 v248, s2, 2
	s_nop 1
	v_writelane_b32 v248, s3, 3
	s_mov_b64 s[2:3], exec
	v_writelane_b32 v248, s4, 4
	s_nop 1
	v_writelane_b32 v248, s5, 5
	s_and_b64 s[4:5], s[2:3], s[4:5]
	s_mov_b64 exec, s[4:5]
	s_cbranch_execz .LBB0_2
	v_mov_b32_e32 v2, 0
	v_mov_b32_e32 v3, v2
	v_mov_b32_e32 v4, v2
	v_mov_b32_e32 v5, v2
	v_mov_b32_e32 v6, 0x12000
	ds_write_b128 v6, v[2:5]

.LBB0_746:
	s_or_b64 exec, exec, s[0:1]
	s_mov_b32 s98, 1
	s_branch .LBB0_770
.Lgf0_gates:
	v_readlane_b32 s0, v248, 0
	s_cmpk_gt_u32 s0, 0x8ff
	s_cbranch_scc1 .LBB0_757
	v_readlane_b32 s0, v248, 0
	s_lshr_b32 s4, s0, 3
	s_and_b32 s0, s0, 7
	s_add_i32 s1, s0, 0xfffc
	s_and_b32 s1, s1, 0xffff
	v_lshlrev_b32_e32 v2, 4, v1
	s_lshr_b32 s5, s50, 3
	s_min_u32 s6, s0, s1
	v_and_b32_e32 v66, 0x70, v2
	v_mov_b32_e32 v67, 0
	s_cmp_gt_u32 s0, 3
	v_lshl_add_u64 v[2:3], s[82:83], 0, v[66:67]
	s_mov_b64 s[0:1], 0x8f00000
	v_lshl_add_u64 v[68:69], v[2:3], 0, s[0:1]
	s_mov_b64 s[0:1], 0xb100000
	v_lshl_add_u64 v[70:71], v[2:3], 0, s[0:1]
	v_lshrrev_b32_e32 v2, 1, v1
	v_and_b32_e32 v95, 0x1c0, v2
	v_lshrrev_b32_e32 v91, 3, v1
	v_or_b32_e32 v2, v95, v132
	s_movk_i32 s0, 0x90
	v_mad_u32_u24 v96, v2, s0, v34
	v_mul_u32_u24_e32 v2, 0x48, v91
	v_and_b32_e32 v90, 0x5f, v1
	v_lshl_add_u32 v98, v2, 1, v66
	v_mov_b32_e32 v35, v67
	s_mul_i32 s6, s6, 6
	s_mov_b32 s7, 0
	s_cselect_b32 s8, 48, 0
	v_add_u32_e32 v92, 32, v91
	v_add_u32_e32 v93, 64, v91
	v_add_u32_e32 v94, 0x60, v91
	v_mad_u32_u24 v97, v90, s0, v34
	v_add_u32_e32 v99, 0x9000, v98
	v_lshl_add_u64 v[72:73], s[82:83], 0, v[34:35]
	s_mov_b64 s[0:1], 0x8000
	v_mov_b32_e32 v100, 0xc00000
	s_mov_b32 s9, s4
	s_mov_b32 s2, s4
	s_branch .LBB0_749

.LBB0_757:
	s_cmp_lt_i32 s53, 6
	s_branch .LBB0_825
	s_cmp_eq_u32 s54, 0
	s_cbranch_scc1 .LBB0_770
	v_lshrrev_b32_e32 v2, 20, v0
	v_lshrrev_b32_e32 v3, 10, v0
	v_or_b32_e32 v2, v3, v2
	s_movk_i32 s0, 0x3ff
	v_and_or_b32 v2, v2, s0, v1
	v_cmp_eq_u32_e32 vcc, 0, v2
	s_waitcnt vmcnt(63) expcnt(7) lgkmcnt(15)
	s_barrier
	s_and_saveexec_b64 s[0:1], vcc
	s_cbranch_execz .LBB0_769
	v_readlane_b32 s2, v248, 2
	v_readlane_b32 s3, v248, 3
	buffer_wbl2 sc1
	s_waitcnt vmcnt(0)
	s_load_dwordx2 s[2:3], s[2:3], 0x58
	v_mov_b32_e32 v4, 0
	s_mov_b64 s[4:5], exec
	v_mbcnt_lo_u32_b32 v3, s4, 0
	v_mbcnt_hi_u32_b32 v3, s5, v3
	s_waitcnt lgkmcnt(0)
	global_load_dword v2, v4, s[2:3] offset:40
	v_cmp_eq_u32_e32 vcc, 0, v3
	s_and_saveexec_b64 s[6:7], vcc
	s_cbranch_execz .LBB0_762
	s_bcnt1_i32_b64 s4, s[4:5]
	v_mov_b32_e32 v5, s4
	global_atomic_add v5, v4, v5, s[2:3] offset:32 sc0

.LBB0_824:
	s_cmp_lg_u32 s98, 0
	s_cbranch_scc0 .Lgf0_nb
	s_mov_b32 s98, 0
	s_branch .Lgf0_gates

.LBB0_825:
	s_cmp_gt_i32 s52, 5
	s_cselect_b64 s[0:1], -1, 0
	s_cmp_lt_i32 s53, 6
	s_cselect_b64 s[2:3], -1, 0
	s_or_b64 s[0:1], s[0:1], s[2:3]
	s_and_b64 vcc, exec, s[0:1]
	s_cbranch_vccnz .LBB0_897
	v_readlane_b32 s0, v248, 0
	s_cmpk_lt_u32 s0, 0x100
	s_cbranch_scc1 .LBB0_829
	v_lshlrev_b32_e32 v2, 4, v1
	v_and_b32_e32 v74, 0x70, v2
	v_mov_b32_e32 v75, 0
	v_lshl_add_u64 v[2:3], s[82:83], 0, v[74:75]
	s_mov_b64 s[6:7], 0xb000000
	v_lshl_add_u64 v[76:77], v[2:3], 0, s[6:7]
	s_mov_b64 s[6:7], 0xc900000
	v_lshl_add_u64 v[78:79], v[2:3], 0, s[6:7]
	v_lshrrev_b32_e32 v2, 1, v1
	v_readlane_b32 s4, v248, 0
	v_and_b32_e32 v97, 0x1c0, v2
	s_lshr_b32 s2, s4, 3
	s_addk_i32 s2, 0xffe0
	s_lshr_b32 s3, s50, 3
	s_lshr_b32 s3, s3, 1
	v_lshrrev_b32_e32 v93, 3, v1
	v_and_or_b32 v3, v1, 31, v97
	v_and_b32_e32 v2, 16, v2
	s_movk_i32 s5, 0x90
	s_add_u32 s0, s82, 0x4800000
	v_mad_u32_u24 v98, v3, s5, v2
	v_mul_u32_u24_e32 v3, 0x48, v93
	s_addc_u32 s1, s83, 0
	v_lshl_add_u32 v100, v3, 1, v74
	v_lshlrev_b32_e32 v74, 1, v97
	v_and_b32_e32 v92, 0x5f, v1
	s_and_b32 s4, s4, 7
	v_lshl_add_u64 v[4:5], s[0:1], 0, v[74:75]
	v_mov_b32_e32 v3, v75
	s_mul_i32 s4, s4, 12
	v_add_u32_e32 v94, 32, v93
	v_add_u32_e32 v95, 64, v93
	v_add_u32_e32 v96, 0x60, v93
	v_mad_u32_u24 v99, v92, s5, v2
	v_add_u32_e32 v101, 0x9000, v100
	v_lshl_add_u64 v[80:81], v[4:5], 0, v[2:3]
	v_lshl_add_u64 v[82:83], s[0:1], 0, v[2:3]
	s_mov_b32 s1, 0
	s_mov_b32 s5, s2
	s_mov_b32 s0, s2
	s_mov_b32 s6, 0

.Lgf1_gates:
	v_readlane_b32 s0, v248, 0
	s_cmpk_gt_u32 s0, 0x8ff
	s_cbranch_scc1 .LBB0_1649
	v_readlane_b32 s0, v248, 0
	s_lshr_b32 s4, s0, 3
	s_and_b32 s0, s0, 7
	s_add_i32 s1, s0, 0xfffc
	s_and_b32 s1, s1, 0xffff
	v_lshlrev_b32_e32 v2, 4, v1
	s_lshr_b32 s5, s50, 3
	s_min_u32 s6, s0, s1
	v_and_b32_e32 v66, 0x70, v2
	v_mov_b32_e32 v67, 0
	s_cmp_gt_u32 s0, 3
	v_lshl_add_u64 v[2:3], s[82:83], 0, v[66:67]
	s_mov_b64 s[0:1], 0xa000000
	v_lshl_add_u64 v[68:69], v[2:3], 0, s[0:1]
	s_mov_b64 s[0:1], 0xb100000
	v_lshl_add_u64 v[70:71], v[2:3], 0, s[0:1]
	v_lshrrev_b32_e32 v2, 1, v1
	v_and_b32_e32 v95, 0x1c0, v2
	v_lshrrev_b32_e32 v91, 3, v1
	v_or_b32_e32 v2, v95, v132
	s_movk_i32 s0, 0x90
	v_mad_u32_u24 v96, v2, s0, v34
	v_mul_u32_u24_e32 v2, 0x48, v91
	v_and_b32_e32 v90, 0x5f, v1
	v_lshl_add_u32 v98, v2, 1, v66
	v_mov_b32_e32 v35, v67
	s_mul_i32 s6, s6, 6
	s_mov_b32 s7, 0
	s_cselect_b32 s8, 48, 0
	v_add_u32_e32 v92, 32, v91
	v_add_u32_e32 v93, 64, v91
	v_add_u32_e32 v94, 0x60, v91
	v_mad_u32_u24 v97, v90, s0, v34
	v_add_u32_e32 v99, 0x9000, v98
	v_lshl_add_u64 v[72:73], s[82:83], 0, v[34:35]
	s_mov_b64 s[0:1], 0x8000
	v_mov_b32_e32 v100, 0xc00000
	s_mov_b32 s9, s4
	s_mov_b32 s2, s4
	s_branch .LBB0_1641

.LBB0_1649:
	s_cmp_lt_i32 s53, 13
	s_branch .LBB0_1717
	s_cmp_eq_u32 s54, 0
	s_cbranch_scc1 .LBB0_1662
	v_lshrrev_b32_e32 v2, 20, v0
	v_lshrrev_b32_e32 v3, 10, v0
	v_or_b32_e32 v2, v3, v2
	s_movk_i32 s0, 0x3ff
	v_and_or_b32 v2, v2, s0, v1
	v_cmp_eq_u32_e32 vcc, 0, v2
	s_waitcnt vmcnt(63) expcnt(7) lgkmcnt(15)
	s_barrier
	s_and_saveexec_b64 s[0:1], vcc
	s_cbranch_execz .LBB0_1661
	v_readlane_b32 s2, v248, 2
	v_readlane_b32 s3, v248, 3
	buffer_wbl2 sc1
	s_waitcnt vmcnt(0)
	s_load_dwordx2 s[2:3], s[2:3], 0x58
	v_mov_b32_e32 v4, 0
	s_mov_b64 s[4:5], exec
	v_mbcnt_lo_u32_b32 v3, s4, 0
	v_mbcnt_hi_u32_b32 v3, s5, v3
	s_waitcnt lgkmcnt(0)
	global_load_dword v2, v4, s[2:3] offset:40
	v_cmp_eq_u32_e32 vcc, 0, v3
	s_and_saveexec_b64 s[6:7], vcc
	s_cbranch_execz .LBB0_1654
	s_bcnt1_i32_b64 s4, s[4:5]
	v_mov_b32_e32 v5, s4
	global_atomic_add v5, v4, v5, s[2:3] offset:32 sc0

.LBB0_1717:
	s_cmp_gt_i32 s52, 12
	s_cselect_b64 s[0:1], -1, 0
	s_cmp_lt_i32 s53, 13
	s_cselect_b64 s[2:3], -1, 0
	s_or_b64 s[0:1], s[0:1], s[2:3]
	s_and_b64 vcc, exec, s[0:1]
	s_cbranch_vccnz .LBB0_1789
	v_readlane_b32 s0, v248, 0
	s_cmpk_lt_u32 s0, 0x100
	s_cbranch_scc1 .LBB0_1721
	v_lshlrev_b32_e32 v2, 4, v1
	v_and_b32_e32 v74, 0x70, v2
	v_mov_b32_e32 v75, 0
	v_lshl_add_u64 v[2:3], s[82:83], 0, v[74:75]
	s_mov_b64 s[6:7], 0xb080000
	v_lshl_add_u64 v[76:77], v[2:3], 0, s[6:7]
	s_mov_b64 s[6:7], 0xc900000
	v_lshl_add_u64 v[78:79], v[2:3], 0, s[6:7]
	v_lshrrev_b32_e32 v2, 1, v1
	v_readlane_b32 s4, v248, 0
	v_and_b32_e32 v97, 0x1c0, v2
	s_lshr_b32 s2, s4, 3
	s_addk_i32 s2, 0xffe0
	s_lshr_b32 s3, s50, 3
	s_lshr_b32 s3, s3, 1
	v_lshrrev_b32_e32 v93, 3, v1
	v_and_or_b32 v3, v1, 31, v97
	v_and_b32_e32 v2, 16, v2
	s_movk_i32 s5, 0x90
	s_add_u32 s0, s82, 0x4800000
	v_mad_u32_u24 v98, v3, s5, v2
	v_mul_u32_u24_e32 v3, 0x48, v93
	s_addc_u32 s1, s83, 0
	v_lshl_add_u32 v100, v3, 1, v74
	v_lshlrev_b32_e32 v74, 1, v97
	v_and_b32_e32 v92, 0x5f, v1
	s_and_b32 s4, s4, 7
	v_lshl_add_u64 v[4:5], s[0:1], 0, v[74:75]
	v_mov_b32_e32 v3, v75
	s_mul_i32 s4, s4, 12
	v_add_u32_e32 v94, 32, v93
	v_add_u32_e32 v95, 64, v93
	v_add_u32_e32 v96, 0x60, v93
	v_mad_u32_u24 v99, v92, s5, v2
	v_add_u32_e32 v101, 0x9000, v100
	v_lshl_add_u64 v[80:81], v[4:5], 0, v[2:3]
	v_lshl_add_u64 v[82:83], s[0:1], 0, v[2:3]
	s_mov_b32 s1, 0
	s_mov_b32 s5, s2
	s_mov_b32 s0, s2
	s_mov_b32 s6, 0

	.amdhsa_kernel _Z14fwd_megakernel6Paramsiii
		.amdhsa_group_segment_fixed_size 73744
		.amdhsa_private_segment_fixed_size 0
		.amdhsa_kernarg_size 464
		.amdhsa_user_sgpr_count 2
		.amdhsa_user_sgpr_dispatch_ptr 0
		.amdhsa_user_sgpr_queue_ptr 0
		.amdhsa_user_sgpr_kernarg_segment_ptr 1
		.amdhsa_user_sgpr_dispatch_id 0
		.amdhsa_user_sgpr_kernarg_preload_length 0
		.amdhsa_user_sgpr_kernarg_preload_offset 0
		.amdhsa_user_sgpr_private_segment_size 0
		.amdhsa_uses_dynamic_stack 0
		.amdhsa_enable_private_segment 0
		.amdhsa_system_sgpr_workgroup_id_x 1
		.amdhsa_system_sgpr_workgroup_id_y 0
		.amdhsa_system_sgpr_workgroup_id_z 0
		.amdhsa_system_sgpr_workgroup_info 0
		.amdhsa_system_vgpr_workitem_id 2
		.amdhsa_next_free_vgpr 256
		.amdhsa_next_free_sgpr 102
		.amdhsa_accum_offset 256
		.amdhsa_reserve_vcc 1
		.amdhsa_float_round_mode_32 0
		.amdhsa_float_round_mode_16_64 0
		.amdhsa_float_denorm_mode_32 3
		.amdhsa_float_denorm_mode_16_64 3
		.amdhsa_dx10_clamp 1
		.amdhsa_ieee_mode 1
		.amdhsa_fp16_overflow 0
		.amdhsa_tg_split 0
		.amdhsa_exception_fp_ieee_invalid_op 0
		.amdhsa_exception_fp_denorm_src 0
		.amdhsa_exception_fp_ieee_div_zero 0
		.amdhsa_exception_fp_ieee_overflow 0
		.amdhsa_exception_fp_ieee_underflow 0
		.amdhsa_exception_fp_ieee_inexact 0
		.amdhsa_exception_int_div_zero 0
	.end_amdhsa_kernel

amdhsa.kernels:
  - .agpr_count:     0
    .args:
      - .offset:         0
        .size:           192
        .value_kind:     by_value
      - .offset:         192
        .size:           4
        .value_kind:     by_value
      - .offset:         196
        .size:           4
        .value_kind:     by_value
      - .offset:         200
        .size:           4
        .value_kind:     by_value
      - .offset:         208
        .size:           4
        .value_kind:     hidden_block_count_x
      - .offset:         212
        .size:           4
        .value_kind:     hidden_block_count_y
      - .offset:         216
        .size:           4
        .value_kind:     hidden_block_count_z
      - .offset:         220
        .size:           2
        .value_kind:     hidden_group_size_x
      - .offset:         222
        .size:           2
        .value_kind:     hidden_group_size_y
      - .offset:         224
        .size:           2
        .value_kind:     hidden_group_size_z
      - .offset:         226
        .size:           2
        .value_kind:     hidden_remainder_x
      - .offset:         228
        .size:           2
        .value_kind:     hidden_remainder_y
      - .offset:         230
        .size:           2
        .value_kind:     hidden_remainder_z
      - .offset:         248
        .size:           8
        .value_kind:     hidden_global_offset_x
      - .offset:         256
        .size:           8
        .value_kind:     hidden_global_offset_y
      - .offset:         264
        .size:           8
        .value_kind:     hidden_global_offset_z
      - .offset:         272
        .size:           2
        .value_kind:     hidden_grid_dims
      - .offset:         296
        .size:           8
        .value_kind:     hidden_multigrid_sync_arg
    .group_segment_fixed_size: 73744
    .kernarg_segment_align: 8
    .kernarg_segment_size: 464
    .language:       OpenCL C
    .language_version:
      - 2
      - 0
    .max_flat_workgroup_size: 256
    .name:           _Z14fwd_megakernel6Paramsiii
    .private_segment_fixed_size: 0
    .sgpr_count: 108
    .sgpr_spill_count: 90
    .symbol:         _Z14fwd_megakernel6Paramsiii.kd
    .uniform_work_group_size: 1
    .uses_dynamic_stack: false
    .vgpr_count: 256
    .vgpr_spill_count: 0
    .wavefront_size: 64
